# DeltaNet step B: all 12 K-step ds_read_b128 of a tile issued up front into spare VGPRs, MFMAs behind counted lgkmcnt (was read-wait(0)-mfma x4)
# baseline (speedup 1.0000x reference)
.LBB0_649:
	s_and_b32 s0, s60, 1
	s_add_i32 s64, 16, 0x1c800
	v_mov_b32_e32 v71, v120
	v_mov_b32_e32 v0, v107
	v_mov_b32_e32 v1, v121
	s_cmp_eq_u32 s0, 0
	s_cselect_b64 s[14:15], -1, 0
	v_add_u32_e32 v0, s33, v71
	v_lshlrev_b32_e32 v60, 4, v1
	s_and_b64 s[0:1], s[14:15], exec
	v_mul_lo_u32 v3, v0, s21
	v_add_u32_e32 v0, 16, v60
	s_cselect_b32 s66, 16, s54
	v_add_u32_e32 v69, v0, v3
	v_add_u32_e32 v80, s35, v71
	v_add3_u32 v70, s66, v3, v60
	v_mad_u64_u32 v[86:87], s[0:1], v80, s21, v[0:1]
	ds_read_b128 v[60:63], v69 offset:17408
	ds_read_b128 v[64:67], v70
	ds_read_b128 v[72:75], v86 offset:17408
	ds_read_b128 v[168:171], v69 offset:17472
	ds_read_b128 v[172:175], v70 offset:64
	ds_read_b128 v[176:179], v86 offset:17472
	ds_read_b128 v[180:183], v69 offset:17536
	ds_read_b128 v[184:187], v70 offset:128
	ds_read_b128 v[188:191], v86 offset:17536
	ds_read_b128 v[192:195], v69 offset:17600
	ds_read_b128 v[196:199], v70 offset:192
	ds_read_b128 v[200:203], v86 offset:17600
	s_cselect_b32 s65, s64, s55
	v_lshl_add_u32 v68, v1, 2, s33
	v_lshl_add_u32 v1, v80, 2, s65
	ds_read_b32 v81, v1
	v_lshl_add_u32 v1, v68, 2, s65
	ds_read_b128 v[160:163], v1
	ds_read_b128 v[164:167], v1 offset:256
	v_cmp_ge_i32_e64 s[12:13], v68, v80
	s_waitcnt lgkmcnt(12)
	v_mfma_f32_16x16x32_bf16 v[60:63], v[60:63], v[72:75], 0
	v_mfma_f32_16x16x32_bf16 v[64:67], v[64:67], v[72:75], 0
	s_waitcnt lgkmcnt(9)
	v_mfma_f32_16x16x32_bf16 v[60:63], v[168:171], v[176:179], v[60:63]
	v_mfma_f32_16x16x32_bf16 v[64:67], v[172:175], v[176:179], v[64:67]
	s_waitcnt lgkmcnt(6)
	v_mfma_f32_16x16x32_bf16 v[60:63], v[180:183], v[188:191], v[60:63]
	v_mfma_f32_16x16x32_bf16 v[72:75], v[184:187], v[188:191], v[64:67]
	s_waitcnt lgkmcnt(3)
	v_mfma_f32_16x16x32_bf16 v[64:67], v[192:195], v[200:203], v[60:63]
	v_mfma_f32_16x16x32_bf16 v[60:63], v[196:199], v[200:203], v[72:75]
	s_nop 4
	v_mov_b32_e32 v72, 0
	v_mov_b32_e32 v73, 0
	s_waitcnt lgkmcnt(0)
	s_and_saveexec_b64 s[0:1], s[12:13]
	s_cbranch_execz .LBB0_651
	v_mov_b32_e32 v3, v160
	s_nop 0
	v_sub_f32_e32 v3, v3, v81
	v_mul_f32_e32 v3, 0x3fb8aa3b, v3
	v_exp_f32_e32 v73, v3

.LBB0_677:
	ds_read_b128 v[160:163], v1
	ds_read_b128 v[164:167], v1 offset:256
	v_add_u32_e32 v71, s63, v71
	v_mad_u64_u32 v[96:97], s[0:1], v71, s21, v[0:1]
	ds_read_b128 v[60:63], v69 offset:17408
	ds_read_b128 v[64:67], v70
	ds_read_b128 v[84:87], v96 offset:17408
	ds_read_b128 v[168:171], v69 offset:17472
	ds_read_b128 v[172:175], v70 offset:64
	ds_read_b128 v[176:179], v96 offset:17472
	ds_read_b128 v[180:183], v69 offset:17536
	ds_read_b128 v[184:187], v70 offset:128
	ds_read_b128 v[188:191], v96 offset:17536
	ds_read_b128 v[192:195], v69 offset:17600
	ds_read_b128 v[196:199], v70 offset:192
	ds_read_b128 v[200:203], v96 offset:17600
	v_lshl_add_u32 v0, v71, 2, s65
	v_cmp_ge_i32_e64 s[12:13], v68, v71
	ds_read_b32 v0, v0
	s_waitcnt lgkmcnt(10)
	v_mfma_f32_16x16x32_bf16 v[60:63], v[60:63], v[84:87], 0
	v_mfma_f32_16x16x32_bf16 v[64:67], v[64:67], v[84:87], 0
	s_waitcnt lgkmcnt(7)
	v_mfma_f32_16x16x32_bf16 v[60:63], v[168:171], v[176:179], v[60:63]
	v_mfma_f32_16x16x32_bf16 v[64:67], v[172:175], v[176:179], v[64:67]
	s_waitcnt lgkmcnt(4)
	v_mfma_f32_16x16x32_bf16 v[60:63], v[180:183], v[188:191], v[60:63]
	v_mfma_f32_16x16x32_bf16 v[84:87], v[184:187], v[188:191], v[64:67]
	v_mov_b32_e32 v70, 0
	s_waitcnt lgkmcnt(1)
	v_mfma_f32_16x16x32_bf16 v[64:67], v[192:195], v[200:203], v[60:63]
	v_mov_b32_e32 v69, 0
	v_mfma_f32_16x16x32_bf16 v[60:63], v[196:199], v[200:203], v[84:87]
	s_waitcnt lgkmcnt(0)
	s_and_saveexec_b64 s[0:1], s[12:13]
	s_cbranch_execz .LBB0_679
	v_mov_b32_e32 v69, v160
	s_nop 0
	v_sub_f32_e32 v69, v69, v0
	v_mul_f32_e32 v69, 0x3fb8aa3b, v69
	v_exp_f32_e32 v69, v69
